# P6 split-K fix-up: all 34 loads (27 + 5 partial, 2 epilogue inputs) issued in one batch instead of three dependent groups, stacked on v78
# baseline (speedup 1.0000x reference)
.LBB0_1357:
	s_or_b64 exec, exec, s[88:89]
	s_lshr_b32 s1, s53, 2
	s_and_b32 s0, s53, 3
	v_mov_b32_e32 v130, v0
	s_lshl_b32 s3, s1, 4
	s_lshl_b32 s18, s0, 1
	s_barrier
	s_or_b32 s18, s3, s18
	v_ashrrev_i32_e32 v131, 31, v130
	s_ashr_i32 s51, s50, 31
	v_lshl_add_u64 v[130:131], v[130:131], 4, s[68:69]
	s_or_b32 s46, s18, 8
	s_lshl_b64 s[20:21], s[50:51], 17
	s_mov_b32 s19, s47
	s_lshl_b64 s[88:89], s[46:47], 12
	v_lshl_add_u64 v[132:133], v[130:131], 0, s[20:21]
	s_lshl_b64 s[90:91], s[18:19], 12
	s_or_b32 s46, s18, 1
	v_lshl_add_u64 v[134:135], v[132:133], 0, s[90:91]
	s_add_u32 s92, s90, 8
	s_addc_u32 s93, s91, 0
	s_or_b32 s46, s18, 9
	s_or_b32 s18, s50, 1
	global_load_dwordx2 v[158:159], v[134:135], off sc1
	v_lshl_add_u64 v[134:135], v[132:133], 0, s[92:93]
	s_add_u32 s94, s88, 8
	s_addc_u32 s95, s89, 0
	s_ashr_i32 s19, s18, 31
	global_load_dwordx2 v[160:161], v[134:135], off sc1
	v_lshl_add_u64 v[134:135], v[132:133], 0, s[88:89]
	v_lshl_add_u64 v[132:133], v[132:133], 0, s[94:95]
	s_lshl_b64 s[18:19], s[18:19], 17
	global_load_dwordx2 v[168:169], v[134:135], off sc1
	global_load_dwordx2 v[170:171], v[132:133], off sc1
	v_lshl_add_u64 v[132:133], v[130:131], 0, s[18:19]
	v_lshl_add_u64 v[134:135], v[132:133], 0, s[90:91]
	s_or_b32 s18, s50, 2
	global_load_dwordx2 v[172:173], v[134:135], off sc1
	v_lshl_add_u64 v[134:135], v[132:133], 0, s[92:93]
	s_ashr_i32 s19, s18, 31
	global_load_dwordx2 v[174:175], v[134:135], off sc1
	v_lshl_add_u64 v[134:135], v[132:133], 0, s[88:89]
	v_lshl_add_u64 v[132:133], v[132:133], 0, s[94:95]
	s_lshl_b64 s[18:19], s[18:19], 17
	global_load_dwordx2 v[176:177], v[134:135], off sc1
	global_load_dwordx2 v[178:179], v[132:133], off sc1
	v_lshl_add_u64 v[132:133], v[130:131], 0, s[18:19]
	v_lshl_add_u64 v[134:135], v[132:133], 0, s[90:91]
	s_or_b32 s18, s50, 3
	global_load_dwordx2 v[180:181], v[134:135], off sc1
	v_lshl_add_u64 v[134:135], v[132:133], 0, s[92:93]
	s_ashr_i32 s19, s18, 31
	global_load_dwordx2 v[182:183], v[134:135], off sc1
	v_lshl_add_u64 v[134:135], v[132:133], 0, s[88:89]
	v_lshl_add_u64 v[132:133], v[132:133], 0, s[94:95]
	s_lshl_b64 s[18:19], s[18:19], 17
	global_load_dwordx2 v[194:195], v[134:135], off sc1
	global_load_dwordx2 v[196:197], v[132:133], off sc1
	v_lshl_add_u64 v[132:133], v[130:131], 0, s[18:19]
	v_lshl_add_u64 v[134:135], v[132:133], 0, s[90:91]
	s_or_b32 s18, s50, 4
	global_load_dwordx2 v[198:199], v[134:135], off sc1
	v_lshl_add_u64 v[134:135], v[132:133], 0, s[92:93]
	s_ashr_i32 s19, s18, 31
	global_load_dwordx2 v[200:201], v[134:135], off sc1
	v_lshl_add_u64 v[134:135], v[132:133], 0, s[88:89]
	v_lshl_add_u64 v[132:133], v[132:133], 0, s[94:95]
	s_lshl_b64 s[18:19], s[18:19], 17
	global_load_dwordx2 v[202:203], v[134:135], off sc1
	global_load_dwordx2 v[204:205], v[132:133], off sc1
	v_lshl_add_u64 v[132:133], v[130:131], 0, s[18:19]
	v_lshl_add_u64 v[134:135], v[132:133], 0, s[90:91]
	global_load_dwordx2 v[206:207], v[134:135], off sc1
	v_lshl_add_u64 v[134:135], v[132:133], 0, s[92:93]
	global_load_dwordx2 v[208:209], v[134:135], off sc1
	v_lshl_add_u64 v[134:135], v[132:133], 0, s[88:89]
	global_load_dwordx2 v[210:211], v[134:135], off sc1
	v_lshl_add_u64 v[132:133], v[132:133], 0, s[94:95]
	global_load_dwordx2 v[164:165], v[132:133], off sc1
	s_or_b32 s18, s50, 5
	s_ashr_i32 s19, s18, 31
	s_lshl_b64 s[18:19], s[18:19], 17
	v_lshl_add_u64 v[132:133], v[130:131], 0, s[18:19]
	v_lshl_add_u64 v[134:135], v[132:133], 0, s[90:91]
	s_or_b32 s18, s50, 6
	global_load_dwordx2 v[166:167], v[134:135], off sc1
	v_lshl_add_u64 v[134:135], v[132:133], 0, s[92:93]
	s_ashr_i32 s19, s18, 31
	global_load_dwordx2 v[162:163], v[134:135], off sc1
	v_lshl_add_u64 v[134:135], v[132:133], 0, s[88:89]
	v_lshl_add_u64 v[132:133], v[132:133], 0, s[94:95]
	s_lshl_b64 s[18:19], s[18:19], 17
	global_load_dwordx2 v[148:149], v[134:135], off sc1
	global_load_dwordx2 v[144:145], v[132:133], off sc1
	v_lshl_add_u64 v[132:133], v[130:131], 0, s[18:19]
	v_lshl_add_u64 v[134:135], v[132:133], 0, s[90:91]
	s_or_b32 s18, s50, 7
	global_load_dwordx2 v[146:147], v[134:135], off sc1
	v_lshl_add_u64 v[134:135], v[132:133], 0, s[92:93]
	s_ashr_i32 s19, s18, 31
	global_load_dwordx2 v[142:143], v[134:135], off sc1
	v_lshl_add_u64 v[134:135], v[132:133], 0, s[88:89]
	s_lshl_b64 s[18:19], s[18:19], 17
	global_load_dwordx2 v[140:141], v[134:135], off sc1
	v_lshl_add_u64 v[132:133], v[132:133], 0, s[94:95]
	v_lshl_add_u64 v[130:131], v[130:131], 0, s[18:19]
	global_load_dwordx2 v[2:3], v[132:133], off sc1
	v_lshl_add_u64 v[132:133], v[130:131], 0, s[90:91]
	global_load_dwordx2 v[4:5], v[132:133], off sc1
	v_lshl_add_u64 v[132:133], v[130:131], 0, s[92:93]
	global_load_dwordx2 v[6:7], v[132:133], off sc1
	v_lshl_add_u64 v[132:133], v[130:131], 0, s[88:89]
	global_load_dwordx2 v[8:9], v[132:133], off sc1
	v_lshl_add_u64 v[130:131], v[130:131], 0, s[94:95]
	global_load_dwordx2 v[10:11], v[130:131], off sc1
	v_lshl_add_u32 v12, s1, 7, v185
	v_lshl_add_u32 v12, s12, 8, v12
	v_lshl_or_b32 v12, s0, 4, v12
	v_lshl_or_b32 v14, s14, 7, v189
	v_ashrrev_i32_e32 v13, 31, v12
	v_ashrrev_i32_e32 v15, 31, v14
	v_lshlrev_b64 v[16:17], 10, v[12:13]
	v_lshl_add_u64 v[16:17], v[16:17], 0, v[14:15]
	v_readlane_b32 s0, v255, 0
	v_readlane_b32 s1, v255, 1
	v_lshl_add_u64 v[20:21], s[42:43], 0, v[16:17]
	s_nop 0
	v_lshl_add_u64 v[18:19], v[16:17], 1, s[0:1]
	global_load_dwordx4 v[22:25], v[18:19], off
	global_load_dwordx2 v[26:27], v[20:21], off
	s_lshr_b32 s1, s53, 2
	s_and_b32 s0, s53, 3
	s_waitcnt vmcnt(33)
	v_lshlrev_b32_e32 v212, 16, v158
	v_and_b32_e32 v213, 0xffff0000, v158
	v_lshlrev_b32_e32 v158, 16, v159
	v_and_b32_e32 v159, 0xffff0000, v159
	v_pk_add_f32 v[212:213], v[212:213], 0 op_sel_hi:[1,0]
	v_pk_add_f32 v[158:159], v[158:159], 0 op_sel_hi:[1,0]
	s_waitcnt vmcnt(32)
	v_lshlrev_b32_e32 v214, 16, v160
	v_and_b32_e32 v215, 0xffff0000, v160
	v_lshlrev_b32_e32 v160, 16, v161
	v_and_b32_e32 v161, 0xffff0000, v161
	v_pk_add_f32 v[214:215], v[214:215], 0 op_sel_hi:[1,0]
	v_pk_add_f32 v[160:161], v[160:161], 0 op_sel_hi:[1,0]
	s_waitcnt vmcnt(31)
	v_lshlrev_b32_e32 v216, 16, v168
	s_waitcnt vmcnt(29)
	v_lshlrev_b32_e32 v220, 16, v172
	v_and_b32_e32 v221, 0xffff0000, v172
	v_lshlrev_b32_e32 v172, 16, v173
	v_and_b32_e32 v173, 0xffff0000, v173
	v_and_b32_e32 v217, 0xffff0000, v168
	v_lshlrev_b32_e32 v168, 16, v169
	v_and_b32_e32 v169, 0xffff0000, v169
	v_pk_add_f32 v[158:159], v[158:159], v[172:173]
	v_pk_add_f32 v[172:173], v[212:213], v[220:221]
	s_waitcnt vmcnt(28)
	v_lshlrev_b32_e32 v212, 16, v174
	v_and_b32_e32 v213, 0xffff0000, v174
	v_lshlrev_b32_e32 v174, 16, v175
	v_and_b32_e32 v175, 0xffff0000, v175
	v_pk_add_f32 v[216:217], v[216:217], 0 op_sel_hi:[1,0]
	v_pk_add_f32 v[168:169], v[168:169], 0 op_sel_hi:[1,0]
	v_lshlrev_b32_e32 v218, 16, v170
	v_and_b32_e32 v219, 0xffff0000, v170
	v_lshlrev_b32_e32 v170, 16, v171
	v_and_b32_e32 v171, 0xffff0000, v171
	v_pk_add_f32 v[160:161], v[160:161], v[174:175]
	v_pk_add_f32 v[174:175], v[214:215], v[212:213]
	s_waitcnt vmcnt(27)
	v_lshlrev_b32_e32 v212, 16, v176
	v_and_b32_e32 v213, 0xffff0000, v176
	v_lshlrev_b32_e32 v176, 16, v177
	v_and_b32_e32 v177, 0xffff0000, v177
	v_pk_add_f32 v[218:219], v[218:219], 0 op_sel_hi:[1,0]
	v_pk_add_f32 v[170:171], v[170:171], 0 op_sel_hi:[1,0]
	v_pk_add_f32 v[168:169], v[168:169], v[176:177]
	v_pk_add_f32 v[176:177], v[216:217], v[212:213]
	s_waitcnt vmcnt(26)
	v_lshlrev_b32_e32 v212, 16, v178
	v_and_b32_e32 v213, 0xffff0000, v178
	v_lshlrev_b32_e32 v178, 16, v179
	v_and_b32_e32 v179, 0xffff0000, v179
	v_pk_add_f32 v[170:171], v[170:171], v[178:179]
	v_pk_add_f32 v[178:179], v[218:219], v[212:213]
	s_waitcnt vmcnt(25)
	v_lshlrev_b32_e32 v212, 16, v180
	v_and_b32_e32 v213, 0xffff0000, v180
	v_lshlrev_b32_e32 v180, 16, v181
	v_and_b32_e32 v181, 0xffff0000, v181
	v_pk_add_f32 v[158:159], v[158:159], v[180:181]
	s_waitcnt vmcnt(24)
	v_lshlrev_b32_e32 v180, 16, v182
	v_and_b32_e32 v181, 0xffff0000, v182
	v_lshlrev_b32_e32 v182, 16, v183
	v_and_b32_e32 v183, 0xffff0000, v183
	v_pk_add_f32 v[174:175], v[174:175], v[180:181]
	s_waitcnt vmcnt(23)
	v_lshlrev_b32_e32 v180, 16, v194
	v_and_b32_e32 v181, 0xffff0000, v194
	v_pk_add_f32 v[160:161], v[160:161], v[182:183]
	v_lshlrev_b32_e32 v182, 16, v195
	v_and_b32_e32 v183, 0xffff0000, v195
	v_pk_add_f32 v[176:177], v[176:177], v[180:181]
	s_waitcnt vmcnt(22)
	v_lshlrev_b32_e32 v180, 16, v196
	v_and_b32_e32 v181, 0xffff0000, v196
	v_pk_add_f32 v[172:173], v[172:173], v[212:213]
	v_pk_add_f32 v[168:169], v[168:169], v[182:183]
	v_lshlrev_b32_e32 v182, 16, v197
	v_and_b32_e32 v183, 0xffff0000, v197
	v_pk_add_f32 v[178:179], v[178:179], v[180:181]
	s_waitcnt vmcnt(21)
	v_lshlrev_b32_e32 v180, 16, v198
	v_and_b32_e32 v181, 0xffff0000, v198
	v_pk_add_f32 v[170:171], v[170:171], v[182:183]
	v_lshlrev_b32_e32 v182, 16, v199
	v_and_b32_e32 v183, 0xffff0000, v199
	v_pk_add_f32 v[172:173], v[172:173], v[180:181]
	s_waitcnt vmcnt(20)
	v_lshlrev_b32_e32 v180, 16, v200
	v_and_b32_e32 v181, 0xffff0000, v200
	v_pk_add_f32 v[158:159], v[158:159], v[182:183]
	v_lshlrev_b32_e32 v182, 16, v201
	v_and_b32_e32 v183, 0xffff0000, v201
	v_pk_add_f32 v[174:175], v[174:175], v[180:181]
	s_waitcnt vmcnt(19)
	v_lshlrev_b32_e32 v180, 16, v202
	v_and_b32_e32 v181, 0xffff0000, v202
	v_pk_add_f32 v[160:161], v[160:161], v[182:183]
	v_lshlrev_b32_e32 v182, 16, v203
	v_and_b32_e32 v183, 0xffff0000, v203
	v_pk_add_f32 v[176:177], v[176:177], v[180:181]
	s_waitcnt vmcnt(18)
	v_lshlrev_b32_e32 v180, 16, v204
	v_and_b32_e32 v181, 0xffff0000, v204
	v_pk_add_f32 v[168:169], v[168:169], v[182:183]
	v_lshlrev_b32_e32 v182, 16, v205
	v_and_b32_e32 v183, 0xffff0000, v205
	v_pk_add_f32 v[178:179], v[178:179], v[180:181]
	s_waitcnt vmcnt(17)
	v_lshlrev_b32_e32 v180, 16, v207
	v_and_b32_e32 v181, 0xffff0000, v207
	v_pk_add_f32 v[182:183], v[170:171], v[182:183]
	v_lshlrev_b32_e32 v170, 16, v206
	v_and_b32_e32 v171, 0xffff0000, v206
	v_pk_add_f32 v[180:181], v[158:159], v[180:181]
	s_waitcnt vmcnt(16)
	v_lshlrev_b32_e32 v158, 16, v208
	v_and_b32_e32 v159, 0xffff0000, v208
	s_lshl_b32 s3, s12, 8
	s_lshl_b32 s1, s1, 7
	v_pk_add_f32 v[172:173], v[172:173], v[170:171]
	v_lshlrev_b32_e32 v170, 16, v209
	v_and_b32_e32 v171, 0xffff0000, v209
	v_pk_add_f32 v[174:175], v[174:175], v[158:159]
	s_waitcnt vmcnt(15)
	v_lshlrev_b32_e32 v158, 16, v210
	v_and_b32_e32 v159, 0xffff0000, v210
	s_add_i32 s1, s1, s3
	v_pk_add_f32 v[194:195], v[160:161], v[170:171]
	v_lshlrev_b32_e32 v160, 16, v211
	v_and_b32_e32 v161, 0xffff0000, v211
	v_pk_add_f32 v[176:177], v[176:177], v[158:159]
	v_add_u32_e32 v158, s1, v185
	v_pk_add_f32 v[196:197], v[168:169], v[160:161]
	v_lshl_or_b32 v160, s0, 4, v158
	v_lshl_or_b32 v158, s14, 7, v189
	v_ashrrev_i32_e32 v161, 31, v160
	v_lshlrev_b64 v[168:169], 10, v[160:161]
	v_ashrrev_i32_e32 v159, 31, v158
	v_readlane_b32 s0, v255, 0
	s_waitcnt vmcnt(14)
	v_lshlrev_b32_e32 v198, 16, v164
	v_lshl_add_u64 v[200:201], v[168:169], 0, v[158:159]
	v_readlane_b32 s1, v255, 1
	v_and_b32_e32 v199, 0xffff0000, v164
	v_pk_add_f32 v[178:179], v[178:179], v[198:199]
	v_lshl_add_u64 v[168:169], v[200:201], 1, s[0:1]
	v_lshl_add_u64 v[198:199], s[42:43], 0, v[200:201]
	v_lshlrev_b32_e32 v164, 16, v165
	v_and_b32_e32 v165, 0xffff0000, v165
	v_pk_add_f32 v[164:165], v[182:183], v[164:165]
	s_waitcnt vmcnt(13)
	v_lshlrev_b32_e32 v182, 16, v166
	v_and_b32_e32 v183, 0xffff0000, v166
	v_lshlrev_b32_e32 v166, 16, v167
	v_and_b32_e32 v167, 0xffff0000, v167
	v_pk_add_f32 v[166:167], v[180:181], v[166:167]
	s_waitcnt vmcnt(12)
	v_lshlrev_b32_e32 v180, 16, v162
	v_and_b32_e32 v181, 0xffff0000, v162
	v_pk_add_f32 v[174:175], v[174:175], v[180:181]
	s_waitcnt vmcnt(11)
	v_lshlrev_b32_e32 v180, 16, v148
	v_and_b32_e32 v181, 0xffff0000, v148
	v_pk_add_f32 v[176:177], v[176:177], v[180:181]
	s_waitcnt vmcnt(10)
	v_lshlrev_b32_e32 v180, 16, v144
	v_and_b32_e32 v181, 0xffff0000, v144
	v_lshlrev_b32_e32 v144, 16, v145
	v_and_b32_e32 v145, 0xffff0000, v145
	v_lshlrev_b32_e32 v162, 16, v163
	v_and_b32_e32 v163, 0xffff0000, v163
	v_pk_add_f32 v[144:145], v[164:165], v[144:145]
	v_pk_add_f32 v[164:165], v[178:179], v[180:181]
	s_waitcnt vmcnt(9)
	v_lshlrev_b32_e32 v178, 16, v146
	v_and_b32_e32 v179, 0xffff0000, v146
	v_lshlrev_b32_e32 v146, 16, v147
	v_and_b32_e32 v147, 0xffff0000, v147
	v_pk_add_f32 v[162:163], v[194:195], v[162:163]
	v_lshlrev_b32_e32 v148, 16, v149
	v_and_b32_e32 v149, 0xffff0000, v149
	v_pk_add_f32 v[146:147], v[166:167], v[146:147]
	s_waitcnt vmcnt(8)
	v_lshlrev_b32_e32 v166, 16, v142
	v_and_b32_e32 v167, 0xffff0000, v142
	v_lshlrev_b32_e32 v142, 16, v143
	v_and_b32_e32 v143, 0xffff0000, v143
	v_pk_add_f32 v[148:149], v[196:197], v[148:149]
	v_pk_add_f32 v[142:143], v[162:163], v[142:143]
	s_waitcnt vmcnt(7)
	v_lshlrev_b32_e32 v162, 16, v140
	v_and_b32_e32 v163, 0xffff0000, v140
	v_lshlrev_b32_e32 v140, 16, v141
	v_and_b32_e32 v141, 0xffff0000, v141
	v_pk_add_f32 v[140:141], v[148:149], v[140:141]
	s_waitcnt vmcnt(6)
	v_mov_b32_e32 v136, v2
	v_mov_b32_e32 v137, v3
	v_lshlrev_b32_e32 v148, 16, v136
	v_and_b32_e32 v149, 0xffff0000, v136
	v_lshlrev_b32_e32 v136, 16, v137
	v_and_b32_e32 v137, 0xffff0000, v137
	v_pk_add_f32 v[136:137], v[144:145], v[136:137]
	s_waitcnt vmcnt(5)
	v_mov_b32_e32 v138, v4
	v_mov_b32_e32 v139, v5
	v_lshlrev_b32_e32 v144, 16, v138
	v_and_b32_e32 v145, 0xffff0000, v138
	v_lshlrev_b32_e32 v138, 16, v139
	v_and_b32_e32 v139, 0xffff0000, v139
	v_pk_add_f32 v[166:167], v[174:175], v[166:167]
	v_pk_add_f32 v[138:139], v[146:147], v[138:139]
	s_waitcnt vmcnt(4)
	v_mov_b32_e32 v134, v6
	v_mov_b32_e32 v135, v7
	v_lshlrev_b32_e32 v146, 16, v134
	v_and_b32_e32 v147, 0xffff0000, v134
	v_lshlrev_b32_e32 v134, 16, v135
	v_and_b32_e32 v135, 0xffff0000, v135
	v_pk_add_f32 v[162:163], v[176:177], v[162:163]
	v_pk_add_f32 v[134:135], v[142:143], v[134:135]
	v_pk_add_f32 v[142:143], v[166:167], v[146:147]
	s_waitcnt vmcnt(3)
	v_mov_b32_e32 v132, v8
	v_mov_b32_e32 v133, v9
	v_lshlrev_b32_e32 v146, 16, v132
	v_and_b32_e32 v147, 0xffff0000, v132
	v_lshlrev_b32_e32 v132, 16, v133
	v_and_b32_e32 v133, 0xffff0000, v133
	v_pk_add_f32 v[148:149], v[164:165], v[148:149]
	v_pk_add_f32 v[132:133], v[140:141], v[132:133]
	v_pk_add_f32 v[140:141], v[162:163], v[146:147]
	s_waitcnt vmcnt(2)
	v_mov_b32_e32 v130, v10
	v_mov_b32_e32 v131, v11
	v_lshlrev_b32_e32 v146, 16, v130
	v_and_b32_e32 v147, 0xffff0000, v130
	v_lshlrev_b32_e32 v130, 16, v131
	v_and_b32_e32 v131, 0xffff0000, v131
	v_pk_add_f32 v[130:131], v[136:137], v[130:131]
	v_pk_add_f32 v[136:137], v[148:149], v[146:147]
	v_mul_f32_e32 v140, 0xbfb8aa3b, v140
	v_exp_f32_e32 v140, v140
	v_mul_f32_e32 v136, 0xbfb8aa3b, v136
	v_exp_f32_e32 v136, v136
	v_mul_f32_e32 v141, 0xbfb8aa3b, v141
	v_exp_f32_e32 v141, v141
	v_mul_f32_e32 v137, 0xbfb8aa3b, v137
	v_exp_f32_e32 v137, v137
	v_mul_f32_e32 v132, 0xbfb8aa3b, v132
	v_exp_f32_e32 v132, v132
	v_mul_f32_e32 v130, 0xbfb8aa3b, v130
	v_add_f32_e32 v140, 1.0, v140
	v_pk_add_f32 v[172:173], v[172:173], v[182:183]
	v_exp_f32_e32 v130, v130
	v_mul_f32_e32 v133, 0xbfb8aa3b, v133
	v_rcp_f32_e32 v140, v140
	v_add_f32_e32 v136, 1.0, v136
	v_pk_add_f32 v[172:173], v[172:173], v[178:179]
	s_waitcnt vmcnt(0)
	v_mov_b32_e32 v168, v22
	v_mov_b32_e32 v169, v23
	v_mov_b32_e32 v170, v24
	v_mov_b32_e32 v171, v25
	v_mov_b32_e32 v198, v26
	v_mov_b32_e32 v199, v27
	v_cvt_f32_ubyte0_e32 v166, v198
	v_exp_f32_e32 v133, v133
	v_mul_f32_e32 v131, 0xbfb8aa3b, v131
	v_rcp_f32_e32 v136, v136
	v_add_f32_e32 v141, 1.0, v141
	v_pk_add_f32 v[144:145], v[172:173], v[144:145]
	v_lshlrev_b32_e32 v162, 16, v170
	v_and_b32_e32 v163, 0xffff0000, v170
	v_mul_f32_e32 v166, 0x3b808081, v166
	v_cvt_f32_ubyte0_e32 v170, v199
	v_exp_f32_e32 v131, v131
	v_rcp_f32_e32 v141, v141
	v_add_f32_e32 v137, 1.0, v137
	v_lshlrev_b32_e32 v146, 16, v168
	v_cvt_f32_ubyte1_e32 v167, v198
	v_mul_f32_e32 v170, 0x3b808081, v170
	v_rcp_f32_e32 v137, v137
	v_add_f32_e32 v132, 1.0, v132
	v_mul_f32_e32 v144, v166, v144
	v_lshlrev_b32_e32 v164, 16, v171
	v_and_b32_e32 v165, 0xffff0000, v171
	v_mul_f32_e32 v167, 0x3b808081, v167
	v_cvt_f32_ubyte1_e32 v171, v199
	v_rcp_f32_e32 v132, v132
	v_add_f32_e32 v130, 1.0, v130
	v_fmac_f32_e32 v146, v144, v140
	v_mul_f32_e32 v140, v170, v142
	v_and_b32_e32 v147, 0xffff0000, v168
	v_cvt_f32_ubyte2_e32 v168, v198
	v_mul_f32_e32 v171, 0x3b808081, v171
	v_rcp_f32_e32 v130, v130
	v_add_f32_e32 v133, 1.0, v133
	v_fmac_f32_e32 v162, v140, v136
	v_mul_f32_e32 v136, v145, v167
	v_mul_f32_e32 v168, 0x3b808081, v168
	v_cvt_f32_ubyte2_e32 v172, v199
	v_rcp_f32_e32 v133, v133
	v_add_f32_e32 v131, 1.0, v131
	v_fmac_f32_e32 v147, v136, v141
	v_mul_f32_e32 v136, v171, v143
	v_lshlrev_b32_e32 v148, 16, v169
	v_and_b32_e32 v149, 0xffff0000, v169
	v_cvt_f32_ubyte3_e32 v169, v198
	v_mul_f32_e32 v172, 0x3b808081, v172
	v_rcp_f32_e32 v131, v131
	v_fmac_f32_e32 v163, v136, v137
	v_mul_f32_e32 v136, v138, v168
	v_mul_f32_e32 v169, 0x3b808081, v169
	v_cvt_f32_ubyte3_e32 v173, v199
	v_fmac_f32_e32 v148, v136, v132
	v_mul_f32_e32 v132, v172, v134
	v_mul_f32_e32 v173, 0x3b808081, v173
	v_fmac_f32_e32 v164, v132, v130
	v_mul_f32_e32 v130, v169, v139
	v_fmac_f32_e32 v149, v130, v133
	v_mul_f32_e32 v130, v173, v135
	v_fmac_f32_e32 v165, v130, v131
	v_cvt_pk_bf16_f32 v130, v146, v147
	v_cvt_pk_bf16_f32 v131, v148, v149
	v_cvt_pk_bf16_f32 v132, v162, v163
	v_cvt_pk_bf16_f32 v133, v164, v165
	s_branch .LBB0_1354
